# PRE: decay table computed by workgroups 0..9 (one slice each) instead of ten passes on workgroup 0
# baseline (speedup 1.0000x reference)
; __device__ __forceinline__ float softplusf(float x) { return x > 20.f ? x : log1pf(expf(x)); }
; __device__ __forceinline__ void ph_pre(const P& p, char* smem) {
;     ...
;   if (blockIdx.x == 0) for (int i = tid; i < 5120; i += 512) p.CL[i] = 8.f * softplusf(-p.lru_lam[i]);
.LBB0_1887:
	s_and_b64 vcc, exec, s[6:7]
	s_cbranch_vccz .LBB0_1936
	s_cmp_lg_u32 s8, 0
	s_cbranch_scc1 .LBB0_1936
	s_waitcnt lgkmcnt(0)
	v_mov_b32_e32 v2, v168
	s_cmp_lt_u32 s84, 10
	s_cselect_b64 s[6:7], -1, 0
	v_cmp_gt_i32_e32 vcc, s95, v2
	s_and_b64 s[8:9], s[6:7], vcc
	s_and_saveexec_b64 s[6:7], s[8:9]
	s_cbranch_execz .LBB0_1894
	v_ashrrev_i32_e32 v3, 31, v2
	v_readlane_b32 s40, v254, 25
	v_readlane_b32 s8, v252, 0
	v_lshlrev_b64 v[6:7], 2, v[2:3]
	v_readlane_b32 s50, v254, 35
	v_readlane_b32 s51, v254, 36
	v_readlane_b32 s9, v252, 1
	v_mov_b32_e32 v0, 0x11ff
	v_lshl_add_u64 v[4:5], s[50:51], 0, v[6:7]
	v_lshl_add_u64 v[6:7], s[8:9], 0, v[6:7]
	s_lshl_b32 s12, s84, 11
	s_mov_b32 s13, 0
	v_lshl_add_u64 v[4:5], v[4:5], 0, s[12:13]
	v_lshl_add_u64 v[6:7], v[6:7], 0, s[12:13]
	s_mov_b64 s[8:9], 0
	v_readlane_b32 s41, v254, 26
	v_readlane_b32 s42, v254, 27
	v_readlane_b32 s43, v254, 28
	v_readlane_b32 s44, v254, 29
	v_readlane_b32 s45, v254, 30
	v_readlane_b32 s46, v254, 31
	v_readlane_b32 s47, v254, 32
	v_readlane_b32 s48, v254, 33
	v_readlane_b32 s49, v254, 34
	v_readlane_b32 s52, v254, 37
	v_readlane_b32 s53, v254, 38
	v_readlane_b32 s54, v254, 39
	v_readlane_b32 s55, v254, 40
	s_branch .LBB0_1892
